# grid barriers P5->P6 and P6->P7 are XCD-local (guarded by a class-to-XCC consistency check cached in LDS)
# speedup vs baseline: 1.0393x; 1.0114x over previous
; #define LAS __attribute__((address_space(3)))
; DI unsigned xb_add(unsigned* p, unsigned v) { return __hip_atomic_fetch_add(p, v, __ATOMIC_RELAXED, __HIP_MEMORY_SCOPE_AGENT); }
; DI unsigned xb_xcc_id() { return (unsigned)__builtin_amdgcn_s_getreg((3 << 11) | 20) & 0xFu; }
; DI XcdBarrier xcd_barrier_post(unsigned* bar, volatile LAS unsigned* st) {
;   XcdBarrier b; b.bar = bar; b.x = xb_xcc_id(); b.st = st;
;   if (threadIdx.x == 0) (void)xb_add(&bar[XB_XCNT(b.x)], 1u);
;   return b;
; }
.LBB0_2:
	s_or_b64 exec, exec, s[4:5]
	s_load_dwordx16 s[36:51], s[0:1], 0x0
	s_add_u32 s96, s26, 0x1e7e1000
	s_waitcnt lgkmcnt(0)
	s_barrier
	s_getreg_b32 s0, hwreg(HW_REG_XCC_ID, 0, 4)
	s_addc_u32 s97, s27, 0
	s_and_b32 s33, s0, 15
	s_and_saveexec_b64 s[0:1], s[94:95]
	s_cbranch_execz .LBB0_5
	s_mov_b64 s[4:5], exec
	v_mbcnt_lo_u32_b32 v1, s4, 0
	v_mbcnt_hi_u32_b32 v1, s5, v1
	v_cmp_eq_u32_e32 vcc, 0, v1
	s_and_b64 s[16:17], exec, vcc
	s_mov_b64 exec, s[16:17]
	s_cbranch_execz .LBB0_5
	s_lshl_b32 s3, s33, 8
	s_bcnt1_i32_b64 s4, s[4:5]
	v_mov_b32_e32 v1, s3
	v_mov_b32_e32 v2, s4
	global_atomic_add v1, v2, s[96:97] offset:1024
	s_and_b32 s3, s2, 7
	s_lshl_b32 s3, s3, 2
	s_add_i32 s3, s3, 0x300
	v_mov_b32_e32 v3, s3
	s_lshl_b32 s3, 1, s33
	v_mov_b32_e32 v4, s3
	global_atomic_or v3, v4, s[96:97]

; DI unsigned xb_ld(unsigned* p) { return __hip_atomic_load(p, __ATOMIC_RELAXED, __HIP_MEMORY_SCOPE_AGENT); }
; DI void xcd_barrier_complete(unsigned* bar, unsigned x, unsigned& nloc, unsigned& nx) {
;   const unsigned G = gridDim.x * gridDim.y * gridDim.z;
;   unsigned sum, cnt, mine, sp = 0u;
;   for (;;) {
;     sum = 0u; cnt = 0u; mine = 0u;
; #pragma unroll
;     for (unsigned j = 0; j < 16; ++j) { const unsigned c = xb_ld(&bar[XB_XCNT(j)]); sum += c; cnt += (c > 0u) ? 1u : 0u; mine = (j == x) ? c : mine; }
;     if (sum == G) break;
;     __builtin_amdgcn_s_sleep(1);
;     if ((++sp & 255u) == 0u) { if (xb_ld(&bar[XB_TMO])) break; if (sp > XB_SPIN_CAP) { atomicAdd(&bar[XB_TMO], 1u); break; } }
;   }
;   nloc = mine > 0u ? mine : 1u; nx = cnt > 0u ? cnt : 1u;
; }
; DI void xcd_barrier(const XcdBarrier& b) {
;   asm volatile("s_waitcnt vmcnt(0)" ::: "memory");
;   __syncthreads();
;   if (threadIdx.x == 0) {
;     unsigned* bar = b.bar;
;     __builtin_amdgcn_s_waitcnt(0);
;     unsigned nloc = b.st[0], nx = b.st[1];
;     if (nloc == 0u) { xcd_barrier_complete(bar, b.x, nloc, nx); b.st[0] = nloc; b.st[1] = nx; }
.LBB0_882:
	s_waitcnt vmcnt(0)
	s_barrier
	s_and_saveexec_b64 s[0:1], s[94:95]
	s_cbranch_execz .LBB0_934
	s_add_i32 s6, 0, 0x23ff0
	v_mov_b32_e32 v0, s6
	s_waitcnt vmcnt(0) expcnt(0) lgkmcnt(0)
	v_mov_b32_e32 v253, 0x1e7e1300
	global_load_dwordx4 v[240:243], v253, s[26:27] sc1
	global_load_dwordx4 v[244:247], v253, s[26:27] offset:16 sc1
	ds_read_b32 v2, v0
	s_add_i32 s6, 0, 0x23ff4
	v_mov_b32_e32 v0, s6
	ds_read_b32 v0, v0
	s_waitcnt lgkmcnt(1)
	v_cmp_ne_u32_e32 vcc, 0, v2
	s_cbranch_vccnz .LBB0_898
	v_readlane_b32 s6, v250, 0
	s_mul_i32 s18, s29, s6
	s_add_u32 s6, s26, 0x1e7e1200
	s_addc_u32 s7, s27, 0
	s_add_u32 s8, s26, 0x1e7e1400
	s_addc_u32 s9, s27, 0
	s_add_u32 s10, s26, 0x1e7e1500
	s_addc_u32 s11, s27, 0
	s_add_u32 s12, s26, 0x1e7e1600
	s_addc_u32 s13, s27, 0
	s_add_u32 s14, s26, 0x1e7e1700
	s_addc_u32 s15, s27, 0
	s_add_u32 s16, s26, 0x1e7e1800
	s_addc_u32 s17, s27, 0
	s_add_u32 s20, s26, 0x1e7e1900
	s_addc_u32 s21, s27, 0
	s_add_u32 s40, s26, 0x1e7e1a00
	s_addc_u32 s41, s27, 0
	s_add_u32 s42, s26, 0x1e7e1b00
	s_addc_u32 s43, s27, 0
	s_add_u32 s44, s26, 0x1e7e1c00
	s_addc_u32 s45, s27, 0
	s_add_u32 s46, s26, 0x1e7e1d00
	s_addc_u32 s47, s27, 0
	s_add_u32 s48, s26, 0x1e7e1e00
	s_addc_u32 s49, s27, 0
	s_add_u32 s50, s26, 0x1e7e1f00
	s_addc_u32 s51, s27, 0
	s_add_u32 s52, s26, 0x1e7e2000
	s_addc_u32 s53, s27, 0
	s_add_u32 s54, s26, 0x1e7e2100
	s_addc_u32 s55, s27, 0
	s_add_u32 s56, s26, 0x1e7e2200
	s_addc_u32 s57, s27, 0
	s_add_u32 s58, s26, 0x1e7e2300
	s_mul_i32 s18, s18, s28
	s_addc_u32 s59, s27, 0
	s_mov_b32 s19, 1
	v_mov_b32_e32 v16, 0
	s_branch .LBB0_886

; DI bool tile_map(int i, int nM, int nN, int& pm, int& pn) {
;   const int G = gridDim.x, c = blockIdx.x;
;   if ((G & 7) == 0 && (nM & 63) == 0) {
;     const int x = c & 7, loc = c >> 3, per = G >> 3, q = i * per + loc, total = (nM >> 3) * nN;
;     if (q >= total) return false;
;     const int g = q / (8 * nN), r = q % (8 * nN);
;     pm = 8 * (g * 8 + (r & 7)) + x; pn = r >> 3; return true;
;   }
;   const long L = (long)i * G + c; if (L >= (long)nM * nN) return false;
;   pm = (int)(L / nN); pn = (int)(L % nN); return true;
; DI void xcd_barrier(const XcdBarrier& b) {
;     ...
;   __syncthreads();
; }
.LBB0_934:
	s_or_b64 exec, exec, s[0:1]
	s_and_saveexec_b64 s[98:99], s[94:95]
	v_add_u32_e32 v248, -1, v240
	v_and_b32_e32 v248, v248, v240
	v_add_u32_e32 v249, -1, v241
	v_and_b32_e32 v249, v249, v241
	v_or_b32_e32 v248, v248, v249
	v_add_u32_e32 v249, -1, v242
	v_and_b32_e32 v249, v249, v242
	v_or_b32_e32 v248, v248, v249
	v_add_u32_e32 v249, -1, v243
	v_and_b32_e32 v249, v249, v243
	v_or_b32_e32 v248, v248, v249
	v_add_u32_e32 v249, -1, v244
	v_and_b32_e32 v249, v249, v244
	v_or_b32_e32 v248, v248, v249
	v_add_u32_e32 v249, -1, v245
	v_and_b32_e32 v249, v249, v245
	v_or_b32_e32 v248, v248, v249
	v_add_u32_e32 v249, -1, v246
	v_and_b32_e32 v249, v249, v246
	v_or_b32_e32 v248, v248, v249
	v_add_u32_e32 v249, -1, v247
	v_and_b32_e32 v249, v249, v247
	v_or_b32_e32 v248, v248, v249
	v_cmp_eq_u32_e32 vcc, 0, v248
	s_nop 1
	v_cndmask_b32_e64 v249, 0, 1, vcc
	v_mov_b32_e32 v253, 0x23ff8
	ds_write_b32 v253, v249
	s_or_b64 exec, exec, s[98:99]
	s_waitcnt vmcnt(25)
	v_mov_b32_e32 v12, v194
	s_waitcnt lgkmcnt(0)
	s_barrier
	s_and_b64 vcc, exec, s[34:35]
	v_readfirstlane_b32 s12, v12
	s_cbranch_vccz .LBB0_938
	s_mov_b64 s[8:9], 0
	s_and_b64 vcc, exec, s[4:5]
	s_mov_b64 s[4:5], 0
	s_cbranch_vccnz .LBB0_937
	s_ashr_i32 s0, s2, 31
	s_lshr_b32 s0, s0, 30
	s_add_i32 s0, s2, s0
	s_ashr_i32 s6, s0, 2
	s_and_b32 s0, s0, -4
	s_sub_i32 s0, s2, s0
	s_mov_b64 s[4:5], -1

; DI unsigned xb_ld(unsigned* p) { return __hip_atomic_load(p, __ATOMIC_RELAXED, __HIP_MEMORY_SCOPE_AGENT); }
; DI unsigned xb_add(unsigned* p, unsigned v) { return __hip_atomic_fetch_add(p, v, __ATOMIC_RELAXED, __HIP_MEMORY_SCOPE_AGENT); }
; #define XB_SPIN(cond, bar) do { unsigned _sp = 0; while (cond) { __builtin_amdgcn_s_sleep(1); \
;     if ((++_sp & 255u) == 0u) { if (xb_ld(&(bar)[XB_TMO])) break; if (_sp > XB_SPIN_CAP) { atomicAdd(&(bar)[XB_TMO], 1u); break; } } } } while (0)
; DI void xcd_barrier(const XcdBarrier& b) {
;     ...
;     const unsigned old = xb_add(&bar[XB_XSUB(b.x)], 1u);
;     const unsigned gen = old / nloc;
;     if (old + 1u == (gen + 1u) * nloc) {
;       __builtin_amdgcn_fence(__ATOMIC_RELEASE, "agent");
;       asm volatile("s_waitcnt vmcnt(0)" ::: "memory");
;       const unsigned og = xb_add(&bar[XB_TOP], 1u);
;       const unsigned tg = og / nx;
;       if (og + 1u == (tg + 1u) * nx) xb_add(&bar[XB_TOPGEN], 1u);
;       else XB_SPIN(xb_ld(&bar[XB_TOPGEN]) == tg, bar);
;       __builtin_amdgcn_fence(__ATOMIC_ACQUIRE, "agent");
;       xb_add(&bar[XB_XGEN(b.x)], 1u);
.LBB0_1016:
	s_andn2_saveexec_b64 s[6:7], s[6:7]
	s_cbranch_execz .LBB0_1036
	s_mov_b64 s[6:7], exec
	v_mov_b32_e32 v253, 0x23ff8
	ds_read_b32 v252, v253
	buffer_wbl2 sc1
	s_waitcnt lgkmcnt(0)
	s_waitcnt vmcnt(0)
	v_cmp_ne_u32_e32 vcc, 0, v252
	s_cbranch_vccnz .LBB0_1033
	v_mbcnt_lo_u32_b32 v1, s6, 0
	v_mbcnt_hi_u32_b32 v1, s7, v1
	v_cmp_eq_u32_e32 vcc, 0, v1
	s_and_saveexec_b64 s[8:9], vcc
	s_cbranch_execz .LBB0_1019
	s_bcnt1_i32_b64 s3, s[6:7]
	v_mov_b32_e32 v2, 0x1e7e4000
	v_mov_b32_e32 v3, s3
	global_atomic_add v2, v2, v3, s[26:27] offset:1024 sc0
